# group seams: thread 0 issues the L1 invalidate on entering the seam (before the store drain and workgroup barrier) instead of after them (on top of v16)
# speedup vs baseline: 1.0067x; 1.0067x over previous
.LBB0_214:
	v_readlane_b32 s75, v250, 21
	v_readlane_b32 s0, v252, 2
	s_or_b32 s8, s75, 2
	v_readlane_b32 s1, v252, 3
	s_cmp_ge_i32 s8, s1
	s_cbranch_scc1 .LBB0_226
	v_readlane_b32 s4, v252, 0
	v_readlane_b32 s5, v252, 1
	s_and_saveexec_b64 s[98:99], s[4:5]
	s_cbranch_execz .Learly_inv_0
	buffer_inv sc1
.Learly_inv_0:
	s_mov_b64 exec, s[98:99]
	s_waitcnt vmcnt(0)
	v_readlane_b32 s4, v252, 0
	v_readlane_b32 s5, v252, 1
	s_barrier
	s_and_saveexec_b64 s[0:1], s[4:5]
	v_readlane_b32 s84, v250, 16
	v_readlane_b32 s54, v250, 19
	v_readlane_b32 s36, v250, 15
	v_readlane_b32 s85, v250, 17
	v_readlane_b32 s37, v250, 18
	s_mov_b32 s81, 0x16000
	s_mov_b64 s[86:87], 0xc00
	v_readlane_b32 s55, v250, 20
	v_readlane_b32 s46, v250, 22
	s_cbranch_execz .LBB0_268
	v_readlane_b32 s4, v251, 63
	s_waitcnt vmcnt(0) expcnt(0) lgkmcnt(0)
	s_nop 0
	v_mov_b32_e32 v2, s4
	ds_read_b32 v4, v2
	v_readlane_b32 s4, v250, 0
	s_waitcnt lgkmcnt(0)
	v_cmp_ne_u32_e32 vcc, 0, v4
	v_mov_b32_e32 v2, s4
	ds_read_b32 v2, v2
	s_cbranch_vccnz .LBB0_232
	s_mov_b32 s11, 1
	v_readlane_b32 s4, v252, 24
	s_branch .LBB0_219

.LBB0_496:
	v_readlane_b32 s0, v252, 2
	s_or_b32 s8, s75, 3
	v_readlane_b32 s1, v252, 3
	s_cmp_ge_i32 s8, s1
	s_cbranch_scc1 .LBB0_538
	v_readlane_b32 s4, v252, 0
	v_readlane_b32 s5, v252, 1
	s_and_saveexec_b64 s[98:99], s[4:5]
	s_cbranch_execz .Learly_inv_1
	buffer_inv sc1
.Learly_inv_1:
	s_mov_b64 exec, s[98:99]
	s_waitcnt vmcnt(0)
	v_readlane_b32 s4, v252, 0
	v_readlane_b32 s5, v252, 1
	s_barrier
	s_and_saveexec_b64 s[0:1], s[4:5]
	s_cbranch_execz .LBB0_537
	v_readlane_b32 s4, v251, 63
	s_waitcnt vmcnt(0) expcnt(0) lgkmcnt(0)
	s_nop 0
	v_mov_b32_e32 v2, s4
	ds_read_b32 v3, v2
	v_readlane_b32 s4, v250, 0
	s_waitcnt lgkmcnt(0)
	v_cmp_ne_u32_e32 vcc, 0, v3
	v_mov_b32_e32 v2, s4
	ds_read_b32 v2, v2
	s_cbranch_vccnz .LBB0_513
	s_mov_b32 s11, 1
	v_readlane_b32 s4, v252, 24
	s_branch .LBB0_501

.LBB0_619:
	v_readlane_b32 s0, v252, 2
	s_add_i32 s8, s75, 4
	v_readlane_b32 s1, v252, 3
	s_cmp_lt_i32 s8, s1
	s_cselect_b64 s[36:37], -1, 0
	s_and_b64 s[0:1], s[20:21], s[36:37]
	s_andn2_b64 vcc, exec, s[0:1]
	s_cbranch_vccnz .LBB0_661
	v_readlane_b32 s4, v252, 0
	v_readlane_b32 s5, v252, 1
	s_and_saveexec_b64 s[98:99], s[4:5]
	s_cbranch_execz .Learly_inv_2
	buffer_inv sc1

.LBB0_761:
	v_readlane_b32 s4, v252, 0
	v_readlane_b32 s5, v252, 1
	s_and_saveexec_b64 s[98:99], s[4:5]
	s_cbranch_execz .Learly_inv_3
	buffer_inv sc1
.Learly_inv_3:
	s_mov_b64 exec, s[98:99]
	s_waitcnt vmcnt(0)
	v_readlane_b32 s4, v252, 0
	v_readlane_b32 s5, v252, 1
	s_waitcnt lgkmcnt(0)
	s_barrier
	s_and_saveexec_b64 s[0:1], s[4:5]
	s_cbranch_execnz .LBB0_762
	s_getpc_b64 s[98:99]

.LBB0_762:
	v_readlane_b32 s4, v251, 63
	s_waitcnt vmcnt(0) expcnt(0) lgkmcnt(0)
	s_nop 0
	v_mov_b32_e32 v2, s4
	ds_read_b32 v4, v2
	v_readlane_b32 s4, v250, 0
	s_waitcnt lgkmcnt(0)
	v_cmp_ne_u32_e32 vcc, 0, v4
	v_mov_b32_e32 v2, s4
	ds_read_b32 v2, v2
	s_cbranch_vccnz .LBB0_777
	s_mov_b32 s8, 1
	v_readlane_b32 s4, v252, 24
	s_branch .LBB0_765
